# combined: chunk-MLP dwordx4 stores and gate loads via permlane16 swap, items re-split 1/4/0/5 with per-chunk LN statistics, P5 stage-1 dt/decay loads 4 lanes per token
# speedup vs baseline: 1.0053x; 1.0053x over previous
.Lcma_pf0:
	global_load_dwordx4 v[100:103], v200, s[46:47]
	global_load_dwordx4 v[116:119], v204, s[48:49]
	global_load_dwordx4 v[104:107], v201, s[46:47]
	global_load_dwordx4 v[120:123], v205, s[48:49]
	global_load_dwordx4 v[108:111], v202, s[46:47]
	global_load_dwordx4 v[124:127], v206, s[48:49]
	global_load_dwordx4 v[112:115], v203, s[46:47]
	global_load_dwordx4 v[128:131], v207, s[48:49]
	global_load_dwordx4 v[164:167], v209, s[14:15]
	global_load_dwordx4 v[168:171], v209, s[16:17]
	global_load_dwordx4 v[172:175], v209, s[16:17] offset:16
	global_load_dwordx4 v[176:179], v209, s[14:15] offset:16
	global_load_dword v236, v210, s[10:11]
	global_load_dwordx4 v[220:223], v218, s[6:7]
	global_load_dwordx4 v[224:227], v218, s[6:7] offset:64
	global_load_dwordx4 v[228:231], v218, s[6:7] offset:128
	global_load_dwordx4 v[232:235], v218, s[6:7] offset:192
	s_waitcnt vmcnt(0)
	s_branch .Lcma_stats

.Lcma_nostat:
.Lcma_copy:
	s_mov_b64 s[12:13], s[6:7]
	v_mov_b32_e32 v0, v100
	v_mov_b32_e32 v1, v101
	v_mov_b32_e32 v2, v102
	v_mov_b32_e32 v3, v103
	v_mov_b32_e32 v4, v104
	v_mov_b32_e32 v5, v105
	v_mov_b32_e32 v6, v106
	v_mov_b32_e32 v7, v107
	v_mov_b32_e32 v8, v108
	v_mov_b32_e32 v9, v109
	v_mov_b32_e32 v10, v110
	v_mov_b32_e32 v11, v111
	v_mov_b32_e32 v12, v112
	v_mov_b32_e32 v13, v113
	v_mov_b32_e32 v14, v114
	v_mov_b32_e32 v15, v115
	v_mov_b32_e32 v16, v116
	v_mov_b32_e32 v17, v117
	v_mov_b32_e32 v18, v118
	v_mov_b32_e32 v19, v119
	v_mov_b32_e32 v20, v120
	v_mov_b32_e32 v21, v121
	v_mov_b32_e32 v22, v122
	v_mov_b32_e32 v23, v123
	v_mov_b32_e32 v24, v124
	v_mov_b32_e32 v25, v125
	v_mov_b32_e32 v26, v126
	v_mov_b32_e32 v27, v127
	v_mov_b32_e32 v28, v128
	v_mov_b32_e32 v29, v129
	v_mov_b32_e32 v30, v130
	v_mov_b32_e32 v31, v131
	v_mov_b32_e32 v38, v164
	v_mov_b32_e32 v39, v165
	v_mov_b32_e32 v40, v166
	v_mov_b32_e32 v41, v167
	v_mov_b32_e32 v42, v168
	v_mov_b32_e32 v43, v169
	v_mov_b32_e32 v44, v170
	v_mov_b32_e32 v45, v171
	v_mov_b32_e32 v46, v172
	v_mov_b32_e32 v47, v173
	v_mov_b32_e32 v48, v174
	v_mov_b32_e32 v49, v175
	v_mov_b32_e32 v50, v176
	v_mov_b32_e32 v51, v177
	v_mov_b32_e32 v52, v178
	v_mov_b32_e32 v53, v179
	v_mov_b32_e32 v70, v220
	v_mov_b32_e32 v71, v221
	v_mov_b32_e32 v72, v222
	v_mov_b32_e32 v73, v223
	v_mov_b32_e32 v74, v224
	v_mov_b32_e32 v75, v225
	v_mov_b32_e32 v76, v226
	v_mov_b32_e32 v77, v227
	v_mov_b32_e32 v78, v228
	v_mov_b32_e32 v79, v229
	v_mov_b32_e32 v80, v230
	v_mov_b32_e32 v81, v231
	v_mov_b32_e32 v82, v232
	v_mov_b32_e32 v83, v233
	v_mov_b32_e32 v84, v234
	v_mov_b32_e32 v85, v235
	v_mov_b32_e32 v86, v236
	s_nop 1
	v_permlane16_swap_b32 v70, v72
	v_permlane16_swap_b32 v71, v73
	v_permlane16_swap_b32 v74, v76
	v_permlane16_swap_b32 v75, v77
	v_permlane16_swap_b32 v78, v80
	v_permlane16_swap_b32 v79, v81
	v_permlane16_swap_b32 v82, v84
	v_permlane16_swap_b32 v83, v85
	s_cmp_gt_u32 s3, 1
	s_cbranch_scc0 .Lcma_nopf
	s_add_i32 s0, s5, 1
	s_and_b32 s1, s0, 7
	s_lshr_b32 s0, s0, 3
	s_lshl_b32 s0, s0, 7
	s_lshl_b32 s10, s1, 8
	s_lshl_b32 s11, s0, 11
	s_add_u32 s11, s11, s10
	s_add_u32 s46, s42, s11
	s_addc_u32 s47, s43, 0
	s_add_u32 s6, s96, s11
	s_addc_u32 s7, s97, 0
	s_lshl_b32 s10, s1, 15
	s_add_u32 s48, s8, s10
	s_addc_u32 s49, s9, 0
	s_lshl_b32 s10, s0, 7
	s_add_u32 s50, s44, s10
	s_addc_u32 s51, s45, 0
	s_lshl_b32 s10, s1, 9
	s_add_u32 s14, s36, s10
	s_addc_u32 s15, s37, 0
	s_add_u32 s16, s38, s10
	s_addc_u32 s17, s39, 0
	s_add_u32 s10, s40, s10
	s_addc_u32 s11, s41, 0
	s_cmp_lg_u32 s1, 0
	s_cbranch_scc1 .Lcma_pf1
	v_readfirstlane_b32 s0, v195
	s_nop 1
	s_cmp_lt_u32 s0, 0x80
	s_cbranch_scc0 .Lcma_pf1
	global_load_dwordx4 v[132:135], v208, s[50:51]
	global_load_dwordx4 v[136:139], v208, s[50:51] offset:16
	global_load_dwordx4 v[140:143], v208, s[50:51] offset:32
	global_load_dwordx4 v[144:147], v208, s[50:51] offset:48
	global_load_dwordx4 v[148:151], v208, s[50:51] offset:64
	global_load_dwordx4 v[152:155], v208, s[50:51] offset:80
	global_load_dwordx4 v[156:159], v208, s[50:51] offset:96
	global_load_dwordx4 v[160:163], v208, s[50:51] offset:112
.Lcma_pf1:
	global_load_dwordx4 v[100:103], v200, s[46:47]
	global_load_dwordx4 v[116:119], v204, s[48:49]
	global_load_dwordx4 v[104:107], v201, s[46:47]
	global_load_dwordx4 v[120:123], v205, s[48:49]
	global_load_dwordx4 v[108:111], v202, s[46:47]
	global_load_dwordx4 v[124:127], v206, s[48:49]
	global_load_dwordx4 v[112:115], v203, s[46:47]
	global_load_dwordx4 v[128:131], v207, s[48:49]
	global_load_dwordx4 v[164:167], v209, s[14:15]
	global_load_dwordx4 v[168:171], v209, s[16:17]
	global_load_dwordx4 v[172:175], v209, s[16:17] offset:16
	global_load_dwordx4 v[176:179], v209, s[14:15] offset:16
	global_load_dword v236, v210, s[10:11]
	global_load_dwordx4 v[220:223], v218, s[6:7]
	global_load_dwordx4 v[224:227], v218, s[6:7] offset:64
	global_load_dwordx4 v[228:231], v218, s[6:7] offset:128
	global_load_dwordx4 v[232:235], v218, s[6:7] offset:192

.LBB0_947:
	s_or_b64 exec, exec, s[0:1]
	s_waitcnt vmcnt(1)
	v_mov_b32_e32 v1, v195
	s_cmpk_lt_i32 s2, 0x200
	s_waitcnt lgkmcnt(0)
	s_barrier
	s_nop 0
	s_nop 0
	s_nop 0
	s_nop 0
	s_nop 0
	s_nop 0
	s_nop 0
	s_nop 0
	s_nop 0
	s_nop 0
	s_nop 0
	s_nop 0
	s_nop 0
	s_nop 0
	s_nop 0
	s_nop 0
	s_cselect_b64 s[4:5], -1, 0
	s_cmpk_gt_i32 s2, 0x1ff
	v_readfirstlane_b32 s3, v1
	s_cbranch_scc1 .LBB0_950
	s_and_b32 s8, s2, 7
	s_bfe_u32 s1, s2, 0x50003
	s_cmpk_gt_i32 s2, 0xff
	s_cbranch_scc0 .LBB0_951
	s_lshl_b32 s0, s8, 1
	s_bfe_u32 s6, s2, 0x10003
	s_or_b32 s0, s0, s6
	s_lshr_b32 s73, s1, 3
	s_or_b32 s0, s0, 64
	s_bfe_u32 s38, s2, 0x20004
	s_cmp_gt_u32 s1, 15
	s_cselect_b32 s6, 0x2800000, 0
	s_lshl_b32 s12, s73, 10
	s_mov_b32 s11, 0
	s_and_b32 s7, s12, 0x400
	s_or_b32 s10, s6, s7
	s_mov_b32 s13, s11
	s_mov_b32 s74, 8
	s_cbranch_execz .LBB0_952
	s_branch .LBB0_953
